# pf4fu_fl with the staggered team group swapped (teams 0-3 delayed ~4us instead of 4-7)
# baseline (speedup 1.0000x reference)
.LBB0_165:
	s_or_b64 exec, exec, s[0:1]
	s_lshr_b32 s97, s75, 2
	s_xor_b32 s97, s97, 1
	s_mul_i32 s97, s97, 4
